# O-proj residual epilogue: second row half's X loads hoisted next to the first half's (one memory round trip per tile instead of two)
# speedup vs baseline: 1.0059x; 1.0059x over previous
.LBB0_125:
	s_add_u32 s54, s27, 0xffffff00
	s_addc_u32 s55, s53, -1
	s_sub_i32 s27, s52, 32
	s_lshr_b32 s27, s27, 3
	s_mul_i32 s27, s27, 6
	s_add_i32 s27, s27, 8
	s_cmp_gt_i32 s52, 31
	s_cselect_b32 s56, s27, 2
	s_ashr_i32 s57, s56, 31
	s_lshl_b64 s[56:57], s[56:57], 12
	v_mov_b32_e32 v0, v249
	s_add_u32 s56, s72, s56
	s_addc_u32 s57, s73, s57
	s_lshl_b32 s27, s67, 8
	v_lshrrev_b32_e32 v130, 2, v0
	s_or_b32 s27, s27, s87
	v_and_b32_e32 v150, 12, v130
	v_or_b32_e32 v146, s27, v150
	v_ashrrev_i32_e32 v147, 31, v146
	s_ashr_i32 s53, s52, 31
	v_lshl_add_u64 v[130:131], v[146:147], 2, s[56:57]
	s_lshl_b64 s[56:57], s[52:53], 19
	s_add_u32 s56, s70, s56
	v_and_or_b32 v148, v0, 15, s74
	v_mov_b32_e32 v149, s88
	s_addc_u32 s57, s71, s57
	v_and_b32_e32 v0, 16, v0
	v_lshl_add_u64 v[146:147], v[146:147], 1, s[56:57]
	v_lshlrev_b64 v[148:149], 11, v[148:149]
	v_add_u32_e32 v151, 12, v150
	v_cmp_eq_u32_e32 vcc, 0, v0
	v_lshl_add_u64 v[146:147], v[146:147], 0, v[148:149]
	v_lshlrev_b32_e32 v148, 1, v150
	v_cndmask_b32_e32 v0, v151, v150, vcc
	v_sub_co_u32_e32 v146, vcc, v146, v148
	v_lshlrev_b32_e32 v0, 1, v0
	s_nop 0
	v_subbrev_co_u32_e32 v147, vcc, 0, v147, vcc
	v_lshl_add_u64 v[158:159], v[146:147], 0, v[0:1]
	s_mov_b32 s27, 0x8000
	v_add_co_u32_e32 v190, vcc, s27, v158
	s_mov_b32 s27, 0x10000
	s_nop 0
	v_addc_co_u32_e32 v191, vcc, 0, v159, vcc
	v_add_co_u32_e32 v162, vcc, s27, v158
	s_mov_b32 s27, 0x18000
	s_nop 0
	v_addc_co_u32_e32 v163, vcc, 0, v159, vcc
	flat_load_dwordx4 v[142:145], v[130:131]
	flat_load_dwordx4 v[138:141], v[130:131] offset:64
	flat_load_dwordx4 v[134:137], v[130:131] offset:128
	s_nop 0
	flat_load_dwordx4 v[130:133], v[130:131] offset:192
	v_add_co_u32_e32 v160, vcc, s27, v158
	flat_load_dwordx4 v[170:173], v[158:159]
	flat_load_dwordx4 v[174:177], v[158:159] offset:64
	v_addc_co_u32_e32 v161, vcc, 0, v159, vcc
	flat_load_dwordx4 v[178:181], v[190:191]
	flat_load_dwordx4 v[182:185], v[190:191] offset:64
	flat_load_dwordx4 v[186:189], v[162:163]
	flat_load_dwordx4 v[154:157], v[162:163] offset:64
	flat_load_dwordx4 v[150:153], v[160:161]
	flat_load_dwordx4 v[146:149], v[160:161] offset:64
	s_mov_b64 s[56:57], 0x40000
	v_lshl_add_u64 v[208:209], v[158:159], 0, s[56:57]
	flat_load_dwordx4 v[216:219], v[208:209]
	flat_load_dwordx4 v[220:223], v[208:209] offset:64
	s_mov_b64 s[56:57], 0x8000
	v_lshl_add_u64 v[208:209], v[208:209], 0, s[56:57]
	flat_load_dwordx4 v[224:227], v[208:209]
	flat_load_dwordx4 v[228:231], v[208:209] offset:64
	v_lshl_add_u64 v[208:209], v[208:209], 0, s[56:57]
	flat_load_dwordx4 v[232:235], v[208:209]
	flat_load_dwordx4 v[240:243], v[208:209] offset:64
	v_lshl_add_u64 v[208:209], v[208:209], 0, s[56:57]
	flat_load_dwordx4 v[244:247], v[208:209]
	flat_load_dwordx4 v[202:205], v[208:209] offset:64
	s_waitcnt vmcnt(0) lgkmcnt(0)
	v_mov_b32_e32 v0, v172
	v_mov_b32_e32 v172, v173
	s_nop 0
	v_permlane16_swap_b32_e32 v170, v0
	v_permlane16_swap_b32_e32 v171, v172
	v_mov_b32_e32 v194, v156
	v_mov_b32_e32 v195, v157
	v_mov_b32_e32 v196, v152
	v_mov_b32_e32 v197, v153
	v_mov_b32_e32 v198, v148
	v_mov_b32_e32 v199, v149
	v_lshlrev_b32_e32 v148, 16, v170
	v_and_b32_e32 v149, 0xffff0000, v170
	v_lshlrev_b32_e32 v152, 16, v171
	v_and_b32_e32 v153, 0xffff0000, v171
	v_lshlrev_b32_e32 v156, 16, v0
	v_and_b32_e32 v157, 0xffff0000, v0
	v_lshlrev_b32_e32 v170, 16, v172
	v_and_b32_e32 v171, 0xffff0000, v172
	v_mov_b32_e32 v192, v176
	v_mov_b32_e32 v193, v177
	v_pk_fma_f32 v[152:153], v[128:129], v[144:145], v[152:153]
	v_pk_fma_f32 v[148:149], v[126:127], v[142:143], v[148:149]
	v_pk_fma_f32 v[176:177], v[124:125], v[140:141], v[170:171]
	v_pk_fma_f32 v[156:157], v[122:123], v[138:139], v[156:157]
	v_cvt_pk_bf16_f32 v170, v148, v149
	v_cvt_pk_bf16_f32 v171, v152, v153
	v_cvt_pk_bf16_f32 v172, v156, v157
	v_cvt_pk_bf16_f32 v173, v176, v177
	v_permlane16_swap_b32_e32 v174, v192
	v_permlane16_swap_b32_e32 v175, v193
	v_permlane16_swap_b32_e32 v170, v172
	v_permlane16_swap_b32_e32 v171, v173
	flat_store_dwordx4 v[158:159], v[170:173]
	v_lshlrev_b32_e32 v148, 16, v174
	v_and_b32_e32 v149, 0xffff0000, v174
	v_lshlrev_b32_e32 v152, 16, v175
	v_and_b32_e32 v153, 0xffff0000, v175
	v_lshlrev_b32_e32 v156, 16, v192
	v_and_b32_e32 v157, 0xffff0000, v192
	v_lshlrev_b32_e32 v170, 16, v193
	v_and_b32_e32 v171, 0xffff0000, v193
	v_pk_fma_f32 v[152:153], v[96:97], v[136:137], v[152:153]
	v_pk_fma_f32 v[148:149], v[94:95], v[134:135], v[148:149]
	v_pk_fma_f32 v[174:175], v[92:93], v[132:133], v[170:171]
	v_pk_fma_f32 v[156:157], v[90:91], v[130:131], v[156:157]
	v_cvt_pk_bf16_f32 v170, v148, v149
	v_cvt_pk_bf16_f32 v171, v152, v153
	v_cvt_pk_bf16_f32 v172, v156, v157
	v_cvt_pk_bf16_f32 v173, v174, v175
	v_permlane16_swap_b32_e32 v178, v180
	v_permlane16_swap_b32_e32 v179, v181
	v_permlane16_swap_b32_e32 v170, v172
	v_permlane16_swap_b32_e32 v171, v173
	flat_store_dwordx4 v[158:159], v[170:173] offset:64
	v_lshlrev_b32_e32 v148, 16, v178
	v_and_b32_e32 v149, 0xffff0000, v178
	v_lshlrev_b32_e32 v152, 16, v179
	v_and_b32_e32 v153, 0xffff0000, v179
	v_lshlrev_b32_e32 v156, 16, v180
	v_and_b32_e32 v157, 0xffff0000, v180
	v_lshlrev_b32_e32 v170, 16, v181
	v_and_b32_e32 v171, 0xffff0000, v181
	v_pk_fma_f32 v[152:153], v[120:121], v[144:145], v[152:153]
	v_pk_fma_f32 v[148:149], v[118:119], v[142:143], v[148:149]
	v_pk_fma_f32 v[174:175], v[116:117], v[140:141], v[170:171]
	v_pk_fma_f32 v[156:157], v[114:115], v[138:139], v[156:157]
	v_cvt_pk_bf16_f32 v170, v148, v149
	v_cvt_pk_bf16_f32 v171, v152, v153
	v_cvt_pk_bf16_f32 v172, v156, v157
	v_cvt_pk_bf16_f32 v173, v174, v175
	v_permlane16_swap_b32_e32 v182, v184
	v_permlane16_swap_b32_e32 v183, v185
	v_permlane16_swap_b32_e32 v170, v172
	v_permlane16_swap_b32_e32 v171, v173
	flat_store_dwordx4 v[190:191], v[170:173]
	v_lshlrev_b32_e32 v148, 16, v182
	v_and_b32_e32 v149, 0xffff0000, v182
	v_lshlrev_b32_e32 v152, 16, v183
	v_and_b32_e32 v153, 0xffff0000, v183
	v_lshlrev_b32_e32 v156, 16, v184
	v_and_b32_e32 v157, 0xffff0000, v184
	v_lshlrev_b32_e32 v170, 16, v185
	v_and_b32_e32 v171, 0xffff0000, v185
	v_pk_fma_f32 v[152:153], v[88:89], v[136:137], v[152:153]
	v_pk_fma_f32 v[148:149], v[86:87], v[134:135], v[148:149]
	v_pk_fma_f32 v[174:175], v[84:85], v[132:133], v[170:171]
	v_pk_fma_f32 v[156:157], v[82:83], v[130:131], v[156:157]
	v_cvt_pk_bf16_f32 v170, v148, v149
	v_cvt_pk_bf16_f32 v171, v152, v153
	v_cvt_pk_bf16_f32 v172, v156, v157
	v_cvt_pk_bf16_f32 v173, v174, v175
	v_permlane16_swap_b32_e32 v186, v188
	v_permlane16_swap_b32_e32 v187, v189
	v_permlane16_swap_b32_e32 v170, v172
	v_permlane16_swap_b32_e32 v171, v173
	flat_store_dwordx4 v[190:191], v[170:173] offset:64
	v_lshlrev_b32_e32 v148, 16, v186
	v_and_b32_e32 v149, 0xffff0000, v186
	v_lshlrev_b32_e32 v152, 16, v187
	v_and_b32_e32 v153, 0xffff0000, v187
	v_lshlrev_b32_e32 v156, 16, v188
	v_and_b32_e32 v157, 0xffff0000, v188
	v_lshlrev_b32_e32 v170, 16, v189
	v_and_b32_e32 v171, 0xffff0000, v189
	v_permlane16_swap_b32_e32 v155, v195
	v_pk_fma_f32 v[152:153], v[112:113], v[144:145], v[152:153]
	v_pk_fma_f32 v[148:149], v[110:111], v[142:143], v[148:149]
	v_pk_fma_f32 v[174:175], v[108:109], v[140:141], v[170:171]
	v_pk_fma_f32 v[156:157], v[106:107], v[138:139], v[156:157]
	v_permlane16_swap_b32_e32 v154, v194
	v_cvt_pk_bf16_f32 v170, v148, v149
	v_cvt_pk_bf16_f32 v171, v152, v153
	v_cvt_pk_bf16_f32 v172, v156, v157
	v_cvt_pk_bf16_f32 v173, v174, v175
	v_lshlrev_b32_e32 v152, 16, v155
	v_and_b32_e32 v153, 0xffff0000, v155
	v_permlane16_swap_b32_e32 v170, v172
	v_permlane16_swap_b32_e32 v171, v173
	v_lshlrev_b32_e32 v148, 16, v154
	v_and_b32_e32 v149, 0xffff0000, v154
	v_pk_fma_f32 v[154:155], v[80:81], v[136:137], v[152:153]
	v_lshlrev_b32_e32 v152, 16, v194
	v_and_b32_e32 v153, 0xffff0000, v194
	v_lshlrev_b32_e32 v156, 16, v195
	v_and_b32_e32 v157, 0xffff0000, v195
	flat_store_dwordx4 v[162:163], v[170:173]
	v_pk_fma_f32 v[148:149], v[78:79], v[134:135], v[148:149]
	v_pk_fma_f32 v[156:157], v[76:77], v[132:133], v[156:157]
	v_pk_fma_f32 v[170:171], v[74:75], v[130:131], v[152:153]
	v_cvt_pk_bf16_f32 v152, v148, v149
	v_cvt_pk_bf16_f32 v153, v154, v155
	v_cvt_pk_bf16_f32 v154, v170, v171
	v_cvt_pk_bf16_f32 v155, v156, v157
	v_permlane16_swap_b32_e32 v150, v196
	v_permlane16_swap_b32_e32 v151, v197
	v_permlane16_swap_b32_e32 v152, v154
	v_permlane16_swap_b32_e32 v153, v155
	flat_store_dwordx4 v[162:163], v[152:155] offset:64
	v_lshlrev_b32_e32 v148, 16, v150
	v_and_b32_e32 v149, 0xffff0000, v150
	v_lshlrev_b32_e32 v150, 16, v151
	v_and_b32_e32 v151, 0xffff0000, v151
	v_lshlrev_b32_e32 v152, 16, v196
	v_and_b32_e32 v153, 0xffff0000, v196
	v_lshlrev_b32_e32 v154, 16, v197
	v_and_b32_e32 v155, 0xffff0000, v197
	v_pk_fma_f32 v[150:151], v[104:105], v[144:145], v[150:151]
	v_pk_fma_f32 v[148:149], v[102:103], v[142:143], v[148:149]
	v_pk_fma_f32 v[154:155], v[100:101], v[140:141], v[154:155]
	v_pk_fma_f32 v[152:153], v[98:99], v[138:139], v[152:153]
	v_cvt_pk_bf16_f32 v148, v148, v149
	v_cvt_pk_bf16_f32 v149, v150, v151
	v_cvt_pk_bf16_f32 v150, v152, v153
	v_cvt_pk_bf16_f32 v151, v154, v155
	v_permlane16_swap_b32_e32 v146, v198
	v_permlane16_swap_b32_e32 v147, v199
	v_permlane16_swap_b32_e32 v148, v150
	v_permlane16_swap_b32_e32 v149, v151
	flat_store_dwordx4 v[160:161], v[148:151]
	v_lshlrev_b32_e32 v152, 16, v199
	v_and_b32_e32 v153, 0xffff0000, v199
	v_lshlrev_b32_e32 v148, 16, v146
	v_and_b32_e32 v149, 0xffff0000, v146
	v_lshlrev_b32_e32 v146, 16, v147
	v_and_b32_e32 v147, 0xffff0000, v147
	v_pk_fma_f32 v[150:151], v[72:73], v[136:137], v[146:147]
	v_pk_fma_f32 v[146:147], v[70:71], v[134:135], v[148:149]
	v_lshlrev_b32_e32 v148, 16, v198
	v_and_b32_e32 v149, 0xffff0000, v198
	v_pk_fma_f32 v[152:153], v[68:69], v[132:133], v[152:153]
	v_pk_fma_f32 v[148:149], v[66:67], v[130:131], v[148:149]
	v_cvt_pk_bf16_f32 v146, v146, v147
	v_cvt_pk_bf16_f32 v147, v150, v151
	v_cvt_pk_bf16_f32 v148, v148, v149
	v_cvt_pk_bf16_f32 v149, v152, v153
	s_nop 0
	v_permlane16_swap_b32_e32 v146, v148
	v_permlane16_swap_b32_e32 v147, v149
	flat_store_dwordx4 v[160:161], v[146:149] offset:64
	s_mov_b32 s27, 0x40000
	v_add_co_u32_e32 v190, vcc, s27, v158
	s_mov_b32 s27, 0x48000
	s_nop 0
	v_addc_co_u32_e32 v191, vcc, 0, v159, vcc
	v_add_co_u32_e32 v192, vcc, s27, v158
	s_mov_b32 s27, 0x50000
	s_nop 0
	v_addc_co_u32_e32 v193, vcc, 0, v159, vcc
	v_add_co_u32_e32 v160, vcc, s27, v158
	s_mov_b64 s[56:57], 0x40000
	s_nop 0
	v_addc_co_u32_e32 v161, vcc, 0, v159, vcc
	s_mov_b32 s27, 0x58000
	v_lshl_add_u64 v[162:163], v[158:159], 0, s[56:57]
	v_add_co_u32_e32 v158, vcc, s27, v158
	v_mov_b32_e32 v170, v216
	v_mov_b32_e32 v171, v217
	v_mov_b32_e32 v172, v218
	v_mov_b32_e32 v173, v219
	v_mov_b32_e32 v174, v220
	v_mov_b32_e32 v175, v221
	v_mov_b32_e32 v176, v222
	v_mov_b32_e32 v177, v223
	v_addc_co_u32_e32 v159, vcc, 0, v159, vcc
	v_mov_b32_e32 v178, v224
	v_mov_b32_e32 v179, v225
	v_mov_b32_e32 v180, v226
	v_mov_b32_e32 v181, v227
	v_mov_b32_e32 v182, v228
	v_mov_b32_e32 v183, v229
	v_mov_b32_e32 v184, v230
	v_mov_b32_e32 v185, v231
	v_mov_b32_e32 v186, v232
	v_mov_b32_e32 v187, v233
	v_mov_b32_e32 v188, v234
	v_mov_b32_e32 v189, v235
	v_mov_b32_e32 v154, v240
	v_mov_b32_e32 v155, v241
	v_mov_b32_e32 v156, v242
	v_mov_b32_e32 v157, v243
	v_mov_b32_e32 v150, v244
	v_mov_b32_e32 v151, v245
	v_mov_b32_e32 v152, v246
	v_mov_b32_e32 v153, v247
	v_mov_b32_e32 v146, v202
	v_mov_b32_e32 v147, v203
	v_mov_b32_e32 v148, v204
	v_mov_b32_e32 v149, v205
	s_waitcnt vmcnt(0) lgkmcnt(0)
	v_mov_b32_e32 v0, v172
	v_mov_b32_e32 v172, v173
	s_nop 0
	v_permlane16_swap_b32_e32 v170, v0
	v_permlane16_swap_b32_e32 v171, v172
	v_mov_b32_e32 v196, v156
	v_mov_b32_e32 v197, v157
	v_mov_b32_e32 v198, v152
	v_mov_b32_e32 v199, v153
	v_mov_b32_e32 v200, v148
	v_mov_b32_e32 v201, v149
	v_lshlrev_b32_e32 v148, 16, v170
	v_and_b32_e32 v149, 0xffff0000, v170
	v_lshlrev_b32_e32 v152, 16, v171
	v_and_b32_e32 v153, 0xffff0000, v171
	v_lshlrev_b32_e32 v156, 16, v0
	v_and_b32_e32 v157, 0xffff0000, v0
	v_lshlrev_b32_e32 v170, 16, v172
	v_and_b32_e32 v171, 0xffff0000, v172
	v_mov_b32_e32 v194, v176
	v_mov_b32_e32 v195, v177
	v_pk_fma_f32 v[152:153], v[64:65], v[144:145], v[152:153]
	v_pk_fma_f32 v[148:149], v[62:63], v[142:143], v[148:149]
	v_pk_fma_f32 v[176:177], v[60:61], v[140:141], v[170:171]
	v_pk_fma_f32 v[156:157], v[58:59], v[138:139], v[156:157]
	v_cvt_pk_bf16_f32 v170, v148, v149
	v_cvt_pk_bf16_f32 v171, v152, v153
	v_cvt_pk_bf16_f32 v172, v156, v157
	v_cvt_pk_bf16_f32 v173, v176, v177
	v_permlane16_swap_b32_e32 v174, v194
	v_permlane16_swap_b32_e32 v175, v195
	v_permlane16_swap_b32_e32 v170, v172
	v_permlane16_swap_b32_e32 v171, v173
	flat_store_dwordx4 v[190:191], v[170:173]
	v_lshlrev_b32_e32 v148, 16, v174
	v_and_b32_e32 v149, 0xffff0000, v174
	v_lshlrev_b32_e32 v152, 16, v175
	v_and_b32_e32 v153, 0xffff0000, v175
	v_lshlrev_b32_e32 v156, 16, v194
	v_and_b32_e32 v157, 0xffff0000, v194
	v_lshlrev_b32_e32 v170, 16, v195
	v_and_b32_e32 v171, 0xffff0000, v195
	v_pk_fma_f32 v[152:153], v[32:33], v[136:137], v[152:153]
	v_pk_fma_f32 v[148:149], v[30:31], v[134:135], v[148:149]
	v_pk_fma_f32 v[174:175], v[28:29], v[132:133], v[170:171]
	v_pk_fma_f32 v[156:157], v[26:27], v[130:131], v[156:157]
	v_cvt_pk_bf16_f32 v170, v148, v149
	v_cvt_pk_bf16_f32 v171, v152, v153
	v_cvt_pk_bf16_f32 v172, v156, v157
	v_cvt_pk_bf16_f32 v173, v174, v175
	v_permlane16_swap_b32_e32 v178, v180
	v_permlane16_swap_b32_e32 v179, v181
	v_permlane16_swap_b32_e32 v170, v172
	v_permlane16_swap_b32_e32 v171, v173
	flat_store_dwordx4 v[162:163], v[170:173] offset:64
	v_lshlrev_b32_e32 v148, 16, v178
	v_and_b32_e32 v149, 0xffff0000, v178
	v_lshlrev_b32_e32 v152, 16, v179
	v_and_b32_e32 v153, 0xffff0000, v179
	v_lshlrev_b32_e32 v156, 16, v180
	v_and_b32_e32 v157, 0xffff0000, v180
	v_lshlrev_b32_e32 v162, 16, v181
	v_and_b32_e32 v163, 0xffff0000, v181
	v_permlane16_swap_b32_e32 v182, v184
	v_permlane16_swap_b32_e32 v183, v185
	v_pk_fma_f32 v[152:153], v[56:57], v[144:145], v[152:153]
	v_pk_fma_f32 v[148:149], v[54:55], v[142:143], v[148:149]
	v_pk_fma_f32 v[162:163], v[52:53], v[140:141], v[162:163]
	v_pk_fma_f32 v[156:157], v[50:51], v[138:139], v[156:157]
	v_cvt_pk_bf16_f32 v170, v148, v149
	v_cvt_pk_bf16_f32 v171, v152, v153
	v_cvt_pk_bf16_f32 v172, v156, v157
	v_cvt_pk_bf16_f32 v173, v162, v163
	v_lshlrev_b32_e32 v148, 16, v182
	v_and_b32_e32 v149, 0xffff0000, v182
	v_lshlrev_b32_e32 v152, 16, v183
	v_and_b32_e32 v153, 0xffff0000, v183
	v_lshlrev_b32_e32 v156, 16, v184
	v_and_b32_e32 v157, 0xffff0000, v184
	v_lshlrev_b32_e32 v162, 16, v185
	v_and_b32_e32 v163, 0xffff0000, v185
	v_permlane16_swap_b32_e32 v186, v188
	v_permlane16_swap_b32_e32 v187, v189
	v_permlane16_swap_b32_e32 v170, v172
	v_permlane16_swap_b32_e32 v171, v173
	v_pk_fma_f32 v[152:153], v[24:25], v[136:137], v[152:153]
	v_pk_fma_f32 v[148:149], v[22:23], v[134:135], v[148:149]
	v_pk_fma_f32 v[162:163], v[20:21], v[132:133], v[162:163]
	v_pk_fma_f32 v[156:157], v[18:19], v[130:131], v[156:157]
	flat_store_dwordx4 v[192:193], v[170:173]
	v_permlane16_swap_b32_e32 v154, v196
	s_nop 0
	v_cvt_pk_bf16_f32 v170, v148, v149
	v_cvt_pk_bf16_f32 v171, v152, v153
	v_cvt_pk_bf16_f32 v172, v156, v157
	v_cvt_pk_bf16_f32 v173, v162, v163
	v_lshlrev_b32_e32 v148, 16, v186
	v_and_b32_e32 v149, 0xffff0000, v186
	v_lshlrev_b32_e32 v152, 16, v187
	v_and_b32_e32 v153, 0xffff0000, v187
	v_permlane16_swap_b32_e32 v155, v197
	v_permlane16_swap_b32_e32 v170, v172
	v_permlane16_swap_b32_e32 v171, v173
	v_pk_fma_f32 v[152:153], v[48:49], v[144:145], v[152:153]
	v_pk_fma_f32 v[148:149], v[46:47], v[142:143], v[148:149]
	flat_store_dwordx4 v[192:193], v[170:173] offset:64
	v_lshlrev_b32_e32 v162, 16, v189
	v_and_b32_e32 v163, 0xffff0000, v189
	v_cvt_pk_bf16_f32 v170, v148, v149
	v_cvt_pk_bf16_f32 v171, v152, v153
	v_lshlrev_b32_e32 v148, 16, v154
	v_and_b32_e32 v149, 0xffff0000, v154
	v_lshlrev_b32_e32 v152, 16, v155
	v_and_b32_e32 v153, 0xffff0000, v155
	v_permlane16_swap_b32_e32 v150, v198
	v_permlane16_swap_b32_e32 v151, v199
	v_pk_fma_f32 v[162:163], v[44:45], v[140:141], v[162:163]
	v_pk_fma_f32 v[154:155], v[16:17], v[136:137], v[152:153]
	v_pk_fma_f32 v[148:149], v[14:15], v[134:135], v[148:149]
	v_lshlrev_b32_e32 v152, 16, v196
	v_and_b32_e32 v153, 0xffff0000, v196
	v_cvt_pk_bf16_f32 v173, v162, v163
	v_pk_fma_f32 v[162:163], v[10:11], v[130:131], v[152:153]
	v_cvt_pk_bf16_f32 v152, v148, v149
	v_lshlrev_b32_e32 v148, 16, v150
	v_and_b32_e32 v149, 0xffff0000, v150
	v_lshlrev_b32_e32 v150, 16, v151
	v_and_b32_e32 v151, 0xffff0000, v151
	v_pk_fma_f32 v[144:145], v[40:41], v[144:145], v[150:151]
	v_pk_fma_f32 v[142:143], v[38:39], v[142:143], v[148:149]
	v_lshlrev_b32_e32 v148, 16, v198
	v_and_b32_e32 v149, 0xffff0000, v198
	v_lshlrev_b32_e32 v150, 16, v199
	v_and_b32_e32 v151, 0xffff0000, v199
	v_lshlrev_b32_e32 v156, 16, v188
	v_and_b32_e32 v157, 0xffff0000, v188
	v_pk_fma_f32 v[150:151], v[36:37], v[140:141], v[150:151]
	v_pk_fma_f32 v[140:141], v[34:35], v[138:139], v[148:149]
	v_pk_fma_f32 v[156:157], v[42:43], v[138:139], v[156:157]
	v_cvt_pk_bf16_f32 v138, v142, v143
	v_cvt_pk_bf16_f32 v139, v144, v145
	v_cvt_pk_bf16_f32 v140, v140, v141
	v_cvt_pk_bf16_f32 v141, v150, v151
	v_permlane16_swap_b32_e32 v146, v200
	v_permlane16_swap_b32_e32 v147, v201
	v_permlane16_swap_b32_e32 v138, v140
	v_permlane16_swap_b32_e32 v139, v141
	flat_store_dwordx4 v[158:159], v[138:141]
	v_cvt_pk_bf16_f32 v172, v156, v157
	v_lshlrev_b32_e32 v156, 16, v197
	v_lshlrev_b32_e32 v138, 16, v146
	v_and_b32_e32 v139, 0xffff0000, v146
	v_lshlrev_b32_e32 v140, 16, v147
	v_and_b32_e32 v141, 0xffff0000, v147
	v_and_b32_e32 v157, 0xffff0000, v197
	v_pk_fma_f32 v[136:137], v[8:9], v[136:137], v[140:141]
	v_pk_fma_f32 v[134:135], v[6:7], v[134:135], v[138:139]
	v_lshlrev_b32_e32 v138, 16, v200
	v_and_b32_e32 v139, 0xffff0000, v200
	v_lshlrev_b32_e32 v140, 16, v201
	v_and_b32_e32 v141, 0xffff0000, v201
	v_pk_fma_f32 v[156:157], v[12:13], v[132:133], v[156:157]
	v_pk_fma_f32 v[140:141], v[4:5], v[132:133], v[140:141]
	v_pk_fma_f32 v[132:133], v[2:3], v[130:131], v[138:139]
	v_cvt_pk_bf16_f32 v153, v154, v155
	v_cvt_pk_bf16_f32 v154, v162, v163
	v_cvt_pk_bf16_f32 v155, v156, v157
	v_cvt_pk_bf16_f32 v130, v134, v135
	v_cvt_pk_bf16_f32 v131, v136, v137
	v_cvt_pk_bf16_f32 v132, v132, v133
	v_cvt_pk_bf16_f32 v133, v140, v141
	v_permlane16_swap_b32_e32 v170, v172
	v_permlane16_swap_b32_e32 v171, v173
	v_permlane16_swap_b32_e32 v152, v154
	v_permlane16_swap_b32_e32 v153, v155
	v_permlane16_swap_b32_e32 v130, v132
	v_permlane16_swap_b32_e32 v131, v133
	flat_store_dwordx4 v[160:161], v[170:173]
	flat_store_dwordx4 v[160:161], v[152:155] offset:64
	flat_store_dwordx4 v[158:159], v[130:133] offset:64
	s_and_b64 vcc, exec, s[40:41]
	s_movk_i32 s92, 0x2000
	s_cbranch_vccnz .LBB0_128
	s_andn2_b64 vcc, exec, s[44:45]
	s_cbranch_vccnz .LBB0_116
	s_barrier
	s_branch .LBB0_116
